# v24 + L1 invalidate issued before the XCD arrive atomic in the three XCD-local seams; last arriver's fast path is only the release atomic
# baseline (speedup 1.0000x reference)
.LBB0_710:
	buffer_inv sc1
	v_readlane_b32 s4, v246, 3
	s_lshl_b32 s4, s4, 8
	v_readlane_b32 s6, v246, 1
	v_readlane_b32 s7, v246, 2
	s_add_u32 s4, s6, s4
	s_addc_u32 s5, s7, 0
	v_mov_b32_e32 v1, 0x1000
	v_mov_b32_e32 v3, 1
	global_atomic_add v3, v1, v3, s[4:5] offset:1024 sc0
	v_cvt_f32_u32_e32 v1, v2
	v_sub_u32_e32 v4, 0, v2
	v_rcp_iflag_f32_e32 v1, v1
	s_nop 0
	v_mul_f32_e32 v1, 0x4f7ffffe, v1
	v_cvt_u32_f32_e32 v1, v1
	v_mul_lo_u32 v4, v4, v1
	v_mul_hi_u32 v4, v1, v4
	v_add_u32_e32 v1, v1, v4
	s_waitcnt vmcnt(0)
	v_mul_hi_u32 v1, v3, v1
	v_mul_lo_u32 v4, v1, v2
	v_sub_u32_e32 v4, v3, v4
	v_add_u32_e32 v5, 1, v1
	v_cmp_ge_u32_e32 vcc, v4, v2
	v_add_u32_e32 v3, 1, v3
	s_nop 0
	v_cndmask_b32_e32 v1, v1, v5, vcc
	v_sub_u32_e32 v5, v4, v2
	v_cndmask_b32_e32 v4, v4, v5, vcc
	v_add_u32_e32 v5, 1, v1
	v_cmp_ge_u32_e32 vcc, v4, v2
	s_nop 1
	v_cndmask_b32_e32 v1, v1, v5, vcc
	v_mul_lo_u32 v4, v2, v1
	v_add_u32_e32 v2, v4, v2
	v_cmp_ne_u32_e32 vcc, v3, v2
	s_and_saveexec_b64 s[6:7], vcc
	s_xor_b64 s[6:7], exec, s[6:7]
	s_cbranch_execz .LBB0_724
	s_waitcnt lgkmcnt(0)
	v_mov_b32_e32 v0, 0x2000
	global_load_dword v0, v0, s[4:5] offset:1024 sc1
	s_add_u32 s12, s4, 0x2400
	s_addc_u32 s13, s5, 0
	s_waitcnt vmcnt(0)
	v_cmp_eq_u32_e32 vcc, v0, v1
	s_and_saveexec_b64 s[8:9], vcc
	s_cbranch_execz .LBB0_723
	s_add_u32 s10, s76, 0x280200
	s_addc_u32 s11, s77, 0
	s_mov_b32 s24, 1
	s_mov_b64 s[14:15], 0
	v_mov_b32_e32 v0, 0
	s_branch .LBB0_714

.LBB0_724:
	s_andn2_saveexec_b64 s[6:7], s[6:7]
	s_cbranch_execz .LBB0_742
	s_mov_b64 s[6:7], exec
	v_readlane_b32 s98, v246, 60
	s_cmp_eq_u32 s98, 1
	s_cbranch_scc0 .Llnw_slow1
	v_mov_b32_e32 v0, 0x2000
	v_mov_b32_e32 v1, 1
	global_atomic_add v0, v1, s[4:5] offset:1024
	s_branch .LBB0_742

.LBB0_845:
	buffer_inv sc1
	v_readlane_b32 s4, v246, 3
	s_lshl_b32 s4, s4, 8
	v_readlane_b32 s8, v246, 1
	v_readlane_b32 s9, v246, 2
	s_add_u32 s4, s8, s4
	s_addc_u32 s5, s9, 0
	v_mov_b32_e32 v1, 0x1000
	v_mov_b32_e32 v3, 1
	global_atomic_add v3, v1, v3, s[4:5] offset:1024 sc0
	v_cvt_f32_u32_e32 v1, v2
	v_sub_u32_e32 v4, 0, v2
	v_rcp_iflag_f32_e32 v1, v1
	s_nop 0
	v_mul_f32_e32 v1, 0x4f7ffffe, v1
	v_cvt_u32_f32_e32 v1, v1
	v_mul_lo_u32 v4, v4, v1
	v_mul_hi_u32 v4, v1, v4
	v_add_u32_e32 v1, v1, v4
	s_waitcnt vmcnt(0)
	v_mul_hi_u32 v1, v3, v1
	v_mul_lo_u32 v4, v1, v2
	v_sub_u32_e32 v4, v3, v4
	v_add_u32_e32 v5, 1, v1
	v_cmp_ge_u32_e32 vcc, v4, v2
	v_add_u32_e32 v3, 1, v3
	s_nop 0
	v_cndmask_b32_e32 v1, v1, v5, vcc
	v_sub_u32_e32 v5, v4, v2
	v_cndmask_b32_e32 v4, v4, v5, vcc
	v_add_u32_e32 v5, 1, v1
	v_cmp_ge_u32_e32 vcc, v4, v2
	s_nop 1
	v_cndmask_b32_e32 v1, v1, v5, vcc
	v_mul_lo_u32 v4, v2, v1
	v_add_u32_e32 v2, v4, v2
	v_cmp_ne_u32_e32 vcc, v3, v2
	s_and_saveexec_b64 s[8:9], vcc
	s_xor_b64 s[8:9], exec, s[8:9]
	s_cbranch_execz .LBB0_859
	s_waitcnt lgkmcnt(0)
	v_mov_b32_e32 v0, 0x2000
	global_load_dword v0, v0, s[4:5] offset:1024 sc1
	s_add_u32 s14, s4, 0x2400
	s_addc_u32 s15, s5, 0
	s_waitcnt vmcnt(0)
	v_cmp_eq_u32_e32 vcc, v0, v1
	s_and_saveexec_b64 s[10:11], vcc
	s_cbranch_execz .LBB0_858
	s_add_u32 s12, s76, 0x280200
	s_addc_u32 s13, s77, 0
	s_mov_b32 s26, 1
	s_mov_b64 s[16:17], 0
	v_mov_b32_e32 v0, 0
	s_branch .LBB0_849

.LBB0_859:
	s_andn2_saveexec_b64 s[8:9], s[8:9]
	s_cbranch_execz .LBB0_877
	s_mov_b64 s[8:9], exec
	v_readlane_b32 s98, v246, 60
	s_cmp_eq_u32 s98, 1
	s_cbranch_scc0 .Llnw_slow2
	v_mov_b32_e32 v0, 0x2000
	v_mov_b32_e32 v1, 1
	global_atomic_add v0, v1, s[4:5] offset:1024
	s_branch .LBB0_877
